# final-norm rows split 64 / 192 between the K-lo CU and its partner (equal K halves)
# speedup vs baseline: 1.0010x; 1.0010x over previous
.Lw10d:
	v_readlane_b32 s2, v254, 6
	v_readlane_b32 s3, v254, 7
	v_and_b32_e32 v0, 63, v210
	v_readfirstlane_b32 s0, v210
	v_lshlrev_b32_e32 v1, 3, v0
	v_lshlrev_b32_e32 v2, 4, v0
	v_mov_b32_e32 v3, 0x3a800000
	v_mov_b32_e32 v121, 0x358637bd
	s_lshr_b32 s0, s0, 6
	global_load_dwordx4 v[4:7], v2, s[2:3]
	global_load_dwordx4 v[8:11], v2, s[2:3] offset:1024
	global_load_dwordx4 v[12:15], v2, s[2:3] offset:2048
	global_load_dwordx4 v[16:19], v2, s[2:3] offset:3072
	s_and_b32 s1, s101, 0x7f
	s_and_b32 s4, s1, 7
	s_lshr_b32 s5, s1, 4
	s_cmp_lt_u32 s4, 4
	s_cselect_b32 s4, 4, 0xff
	s_cmp_eq_u32 s5, s4
	s_cbranch_scc1 .Lp10a_done
	s_and_b32 s4, s1, 7
	s_mul_i32 s4, s4, 20
	s_lshr_b32 s5, s1, 3
	s_add_i32 s4, s4, s5
	s_lshl_b32 s4, s4, 8
	s_cmp_gt_u32 s0, 7
	s_cbranch_scc1 .Lp10a_done
	s_lshr_b32 s11, s101, 7
	s_cmp_eq_u32 s11, 0
	s_cselect_b32 s10, 2, 6
	s_cselect_b32 s11, 0, 0x40
	s_cselect_b32 s5, 8, 24
	s_mul_i32 s5, s5, s0


	s_add_i32 s5, s5, s11
	s_add_i32 s4, s4, s5

	s_lshl_b32 s5, s4, 11
	s_add_u32 s12, s78, s5
	s_addc_u32 s13, s79, 0
	s_add_u32 s12, s12, 0x2000000
	s_addc_u32 s13, s13, 0
	s_lshl_b32 s5, s4, 12
	s_add_u32 s14, s76, s5
	s_addc_u32 s15, s77, 0
